# code placement: the eight main K-loop heads aligned to 64 bytes
# speedup vs baseline: 1.0014x; 1.0000x over previous
.LBB0_196:
	s_ashr_i32 s45, s44, 31
	s_lshl_b64 s[46:47], s[44:45], 19
	s_add_u32 s46, s59, s46
	s_addc_u32 s47, s61, s47
	s_and_b64 s[48:49], s[6:7], exec
	s_cselect_b32 s9, s47, s53
	s_cselect_b32 s45, s46, s52
	s_ashr_i32 s43, s42, 31
	s_lshl_b64 s[48:49], s[42:43], 19
	s_add_u32 s48, s62, s48
	s_addc_u32 s49, s63, s49
	s_and_b64 s[56:57], s[6:7], exec
	s_cselect_b32 s43, s49, s55
	s_cselect_b32 s51, s48, s54
	s_add_u32 s52, s52, 0x40080
	s_addc_u32 s53, s53, 0
	s_add_u32 s86, s54, 0x100
	v_mov_b32_e32 v0, 0
	s_addc_u32 s87, s55, 0
	s_mov_b32 s88, -2
	v_mov_b32_e32 v1, v0
	v_mov_b32_e32 v2, v0
	v_mov_b32_e32 v3, v0
	v_mov_b32_e32 v4, v0
	v_mov_b32_e32 v5, v0
	v_mov_b32_e32 v6, v0
	v_mov_b32_e32 v7, v0
	v_mov_b32_e32 v16, v0
	v_mov_b32_e32 v17, v0
	v_mov_b32_e32 v18, v0
	v_mov_b32_e32 v19, v0
	v_mov_b32_e32 v20, v0
	v_mov_b32_e32 v21, v0
	v_mov_b32_e32 v22, v0
	v_mov_b32_e32 v23, v0
	v_mov_b32_e32 v32, v0
	v_mov_b32_e32 v33, v0
	v_mov_b32_e32 v34, v0
	v_mov_b32_e32 v35, v0
	v_mov_b32_e32 v36, v0
	v_mov_b32_e32 v37, v0
	v_mov_b32_e32 v38, v0
	v_mov_b32_e32 v39, v0
	v_mov_b32_e32 v48, v0
	v_mov_b32_e32 v49, v0
	v_mov_b32_e32 v50, v0
	v_mov_b32_e32 v51, v0
	v_mov_b32_e32 v52, v0
	v_mov_b32_e32 v53, v0
	v_mov_b32_e32 v54, v0
	v_mov_b32_e32 v55, v0
	v_mov_b32_e32 v8, v0
	v_mov_b32_e32 v9, v0
	v_mov_b32_e32 v10, v0
	v_mov_b32_e32 v11, v0
	v_mov_b32_e32 v12, v0
	v_mov_b32_e32 v13, v0
	v_mov_b32_e32 v14, v0
	v_mov_b32_e32 v15, v0
	v_mov_b32_e32 v24, v0
	v_mov_b32_e32 v25, v0
	v_mov_b32_e32 v26, v0
	v_mov_b32_e32 v27, v0
	v_mov_b32_e32 v28, v0
	v_mov_b32_e32 v29, v0
	v_mov_b32_e32 v30, v0
	v_mov_b32_e32 v31, v0
	v_mov_b32_e32 v40, v0
	v_mov_b32_e32 v41, v0
	v_mov_b32_e32 v42, v0
	v_mov_b32_e32 v43, v0
	v_mov_b32_e32 v44, v0
	v_mov_b32_e32 v45, v0
	v_mov_b32_e32 v46, v0
	v_mov_b32_e32 v47, v0
	v_mov_b32_e32 v56, v0
	v_mov_b32_e32 v57, v0
	v_mov_b32_e32 v58, v0
	v_mov_b32_e32 v59, v0
	v_mov_b32_e32 v60, v0
	v_mov_b32_e32 v61, v0
	v_mov_b32_e32 v62, v0
	v_mov_b32_e32 v63, v0
	v_mov_b32_e32 v64, v0
	v_mov_b32_e32 v65, v0
	v_mov_b32_e32 v66, v0
	v_mov_b32_e32 v67, v0
	v_mov_b32_e32 v68, v0
	v_mov_b32_e32 v69, v0
	v_mov_b32_e32 v70, v0
	v_mov_b32_e32 v71, v0
	v_mov_b32_e32 v80, v0
	v_mov_b32_e32 v81, v0
	v_mov_b32_e32 v82, v0
	v_mov_b32_e32 v83, v0
	v_mov_b32_e32 v84, v0
	v_mov_b32_e32 v85, v0
	v_mov_b32_e32 v86, v0
	v_mov_b32_e32 v87, v0
	v_mov_b32_e32 v96, v0
	v_mov_b32_e32 v97, v0
	v_mov_b32_e32 v98, v0
	v_mov_b32_e32 v99, v0
	v_mov_b32_e32 v100, v0
	v_mov_b32_e32 v101, v0
	v_mov_b32_e32 v102, v0
	v_mov_b32_e32 v103, v0
	v_mov_b32_e32 v128, v0
	v_mov_b32_e32 v129, v0
	v_mov_b32_e32 v130, v0
	v_mov_b32_e32 v131, v0
	v_mov_b32_e32 v132, v0
	v_mov_b32_e32 v133, v0
	v_mov_b32_e32 v134, v0
	v_mov_b32_e32 v135, v0
	v_mov_b32_e32 v72, v0
	v_mov_b32_e32 v73, v0
	v_mov_b32_e32 v74, v0
	v_mov_b32_e32 v75, v0
	v_mov_b32_e32 v76, v0
	v_mov_b32_e32 v77, v0
	v_mov_b32_e32 v78, v0
	v_mov_b32_e32 v79, v0
	v_mov_b32_e32 v88, v0
	v_mov_b32_e32 v89, v0
	v_mov_b32_e32 v90, v0
	v_mov_b32_e32 v91, v0
	v_mov_b32_e32 v92, v0
	v_mov_b32_e32 v93, v0
	v_mov_b32_e32 v94, v0
	v_mov_b32_e32 v95, v0
	v_mov_b32_e32 v112, v0
	v_mov_b32_e32 v113, v0
	v_mov_b32_e32 v114, v0
	v_mov_b32_e32 v115, v0
	v_mov_b32_e32 v116, v0
	v_mov_b32_e32 v117, v0
	v_mov_b32_e32 v118, v0
	v_mov_b32_e32 v119, v0
	v_mov_b32_e32 v136, v0
	v_mov_b32_e32 v137, v0
	v_mov_b32_e32 v138, v0
	v_mov_b32_e32 v139, v0
	v_mov_b32_e32 v140, v0
	v_mov_b32_e32 v141, v0
	v_mov_b32_e32 v142, v0
	v_mov_b32_e32 v143, v0
	.p2alignl 6, 3212836864

.LBB0_590:
	s_ashr_i32 s43, s42, 31
	s_lshl_b64 s[44:45], s[42:43], 19
	s_add_u32 s44, s56, s44
	s_addc_u32 s45, s57, s45
	s_and_b64 s[46:47], s[6:7], exec
	s_cselect_b32 s9, s45, s51
	s_cselect_b32 s43, s44, s50
	s_ashr_i32 s41, s40, 31
	s_lshl_b64 s[46:47], s[40:41], 19
	s_add_u32 s46, s58, s46
	s_addc_u32 s47, s59, s47
	s_and_b64 s[54:55], s[6:7], exec
	s_cselect_b32 s41, s47, s53
	s_cselect_b32 s49, s46, s52
	s_add_u32 s50, s50, 0x40080
	s_addc_u32 s51, s51, 0
	s_add_u32 s73, s52, 0x100
	v_mov_b32_e32 v0, 0
	s_addc_u32 s74, s53, 0
	s_mov_b32 s75, -2
	v_mov_b32_e32 v1, v0
	v_mov_b32_e32 v2, v0
	v_mov_b32_e32 v3, v0
	v_mov_b32_e32 v4, v0
	v_mov_b32_e32 v5, v0
	v_mov_b32_e32 v6, v0
	v_mov_b32_e32 v7, v0
	v_mov_b32_e32 v16, v0
	v_mov_b32_e32 v17, v0
	v_mov_b32_e32 v18, v0
	v_mov_b32_e32 v19, v0
	v_mov_b32_e32 v20, v0
	v_mov_b32_e32 v21, v0
	v_mov_b32_e32 v22, v0
	v_mov_b32_e32 v23, v0
	v_mov_b32_e32 v32, v0
	v_mov_b32_e32 v33, v0
	v_mov_b32_e32 v34, v0
	v_mov_b32_e32 v35, v0
	v_mov_b32_e32 v36, v0
	v_mov_b32_e32 v37, v0
	v_mov_b32_e32 v38, v0
	v_mov_b32_e32 v39, v0
	v_mov_b32_e32 v48, v0
	v_mov_b32_e32 v49, v0
	v_mov_b32_e32 v50, v0
	v_mov_b32_e32 v51, v0
	v_mov_b32_e32 v52, v0
	v_mov_b32_e32 v53, v0
	v_mov_b32_e32 v54, v0
	v_mov_b32_e32 v55, v0
	v_mov_b32_e32 v8, v0
	v_mov_b32_e32 v9, v0
	v_mov_b32_e32 v10, v0
	v_mov_b32_e32 v11, v0
	v_mov_b32_e32 v12, v0
	v_mov_b32_e32 v13, v0
	v_mov_b32_e32 v14, v0
	v_mov_b32_e32 v15, v0
	v_mov_b32_e32 v24, v0
	v_mov_b32_e32 v25, v0
	v_mov_b32_e32 v26, v0
	v_mov_b32_e32 v27, v0
	v_mov_b32_e32 v28, v0
	v_mov_b32_e32 v29, v0
	v_mov_b32_e32 v30, v0
	v_mov_b32_e32 v31, v0
	v_mov_b32_e32 v40, v0
	v_mov_b32_e32 v41, v0
	v_mov_b32_e32 v42, v0
	v_mov_b32_e32 v43, v0
	v_mov_b32_e32 v44, v0
	v_mov_b32_e32 v45, v0
	v_mov_b32_e32 v46, v0
	v_mov_b32_e32 v47, v0
	v_mov_b32_e32 v56, v0
	v_mov_b32_e32 v57, v0
	v_mov_b32_e32 v58, v0
	v_mov_b32_e32 v59, v0
	v_mov_b32_e32 v60, v0
	v_mov_b32_e32 v61, v0
	v_mov_b32_e32 v62, v0
	v_mov_b32_e32 v63, v0
	v_mov_b32_e32 v64, v0
	v_mov_b32_e32 v65, v0
	v_mov_b32_e32 v66, v0
	v_mov_b32_e32 v67, v0
	v_mov_b32_e32 v68, v0
	v_mov_b32_e32 v69, v0
	v_mov_b32_e32 v70, v0
	v_mov_b32_e32 v71, v0
	v_mov_b32_e32 v80, v0
	v_mov_b32_e32 v81, v0
	v_mov_b32_e32 v82, v0
	v_mov_b32_e32 v83, v0
	v_mov_b32_e32 v84, v0
	v_mov_b32_e32 v85, v0
	v_mov_b32_e32 v86, v0
	v_mov_b32_e32 v87, v0
	v_mov_b32_e32 v96, v0
	v_mov_b32_e32 v97, v0
	v_mov_b32_e32 v98, v0
	v_mov_b32_e32 v99, v0
	v_mov_b32_e32 v100, v0
	v_mov_b32_e32 v101, v0
	v_mov_b32_e32 v102, v0
	v_mov_b32_e32 v103, v0
	v_mov_b32_e32 v112, v0
	v_mov_b32_e32 v113, v0
	v_mov_b32_e32 v114, v0
	v_mov_b32_e32 v115, v0
	v_mov_b32_e32 v116, v0
	v_mov_b32_e32 v117, v0
	v_mov_b32_e32 v118, v0
	v_mov_b32_e32 v119, v0
	v_mov_b32_e32 v72, v0
	v_mov_b32_e32 v73, v0
	v_mov_b32_e32 v74, v0
	v_mov_b32_e32 v75, v0
	v_mov_b32_e32 v76, v0
	v_mov_b32_e32 v77, v0
	v_mov_b32_e32 v78, v0
	v_mov_b32_e32 v79, v0
	v_mov_b32_e32 v88, v0
	v_mov_b32_e32 v89, v0
	v_mov_b32_e32 v90, v0
	v_mov_b32_e32 v91, v0
	v_mov_b32_e32 v92, v0
	v_mov_b32_e32 v93, v0
	v_mov_b32_e32 v94, v0
	v_mov_b32_e32 v95, v0
	v_mov_b32_e32 v104, v0
	v_mov_b32_e32 v105, v0
	v_mov_b32_e32 v106, v0
	v_mov_b32_e32 v107, v0
	v_mov_b32_e32 v108, v0
	v_mov_b32_e32 v109, v0
	v_mov_b32_e32 v110, v0
	v_mov_b32_e32 v111, v0
	v_mov_b32_e32 v120, v0
	v_mov_b32_e32 v121, v0
	v_mov_b32_e32 v122, v0
	v_mov_b32_e32 v123, v0
	v_mov_b32_e32 v124, v0
	v_mov_b32_e32 v125, v0
	v_mov_b32_e32 v126, v0
	v_mov_b32_e32 v127, v0
	.p2alignl 6, 3212836864

.LBB0_701:
	s_ashr_i32 s37, s36, 31
	s_lshl_b64 s[38:39], s[36:37], 19
	s_add_u32 s38, s51, s38
	s_addc_u32 s39, s52, s39
	s_and_b64 s[40:41], s[4:5], exec
	s_cselect_b32 s37, s39, s45
	s_cselect_b32 s71, s38, s44
	s_ashr_i32 s25, s24, 31
	s_lshl_b64 s[40:41], s[24:25], 19
	s_add_u32 s40, s53, s40
	s_addc_u32 s41, s54, s41
	s_and_b64 s[48:49], s[4:5], exec
	s_cselect_b32 s25, s41, s47
	s_cselect_b32 s72, s40, s46
	s_add_u32 s44, s44, 0x40080
	s_addc_u32 s45, s45, 0
	s_add_u32 s73, s46, 0x100
	v_mov_b32_e32 v0, 0
	s_addc_u32 s74, s47, 0
	s_mov_b32 s75, -2
	v_mov_b32_e32 v1, v0
	v_mov_b32_e32 v2, v0
	v_mov_b32_e32 v3, v0
	v_mov_b32_e32 v4, v0
	v_mov_b32_e32 v5, v0
	v_mov_b32_e32 v6, v0
	v_mov_b32_e32 v7, v0
	v_mov_b32_e32 v16, v0
	v_mov_b32_e32 v17, v0
	v_mov_b32_e32 v18, v0
	v_mov_b32_e32 v19, v0
	v_mov_b32_e32 v20, v0
	v_mov_b32_e32 v21, v0
	v_mov_b32_e32 v22, v0
	v_mov_b32_e32 v23, v0
	v_mov_b32_e32 v32, v0
	v_mov_b32_e32 v33, v0
	v_mov_b32_e32 v34, v0
	v_mov_b32_e32 v35, v0
	v_mov_b32_e32 v36, v0
	v_mov_b32_e32 v37, v0
	v_mov_b32_e32 v38, v0
	v_mov_b32_e32 v39, v0
	v_mov_b32_e32 v48, v0
	v_mov_b32_e32 v49, v0
	v_mov_b32_e32 v50, v0
	v_mov_b32_e32 v51, v0
	v_mov_b32_e32 v52, v0
	v_mov_b32_e32 v53, v0
	v_mov_b32_e32 v54, v0
	v_mov_b32_e32 v55, v0
	v_mov_b32_e32 v8, v0
	v_mov_b32_e32 v9, v0
	v_mov_b32_e32 v10, v0
	v_mov_b32_e32 v11, v0
	v_mov_b32_e32 v12, v0
	v_mov_b32_e32 v13, v0
	v_mov_b32_e32 v14, v0
	v_mov_b32_e32 v15, v0
	v_mov_b32_e32 v24, v0
	v_mov_b32_e32 v25, v0
	v_mov_b32_e32 v26, v0
	v_mov_b32_e32 v27, v0
	v_mov_b32_e32 v28, v0
	v_mov_b32_e32 v29, v0
	v_mov_b32_e32 v30, v0
	v_mov_b32_e32 v31, v0
	v_mov_b32_e32 v40, v0
	v_mov_b32_e32 v41, v0
	v_mov_b32_e32 v42, v0
	v_mov_b32_e32 v43, v0
	v_mov_b32_e32 v44, v0
	v_mov_b32_e32 v45, v0
	v_mov_b32_e32 v46, v0
	v_mov_b32_e32 v47, v0
	v_mov_b32_e32 v56, v0
	v_mov_b32_e32 v57, v0
	v_mov_b32_e32 v58, v0
	v_mov_b32_e32 v59, v0
	v_mov_b32_e32 v60, v0
	v_mov_b32_e32 v61, v0
	v_mov_b32_e32 v62, v0
	v_mov_b32_e32 v63, v0
	v_mov_b32_e32 v64, v0
	v_mov_b32_e32 v65, v0
	v_mov_b32_e32 v66, v0
	v_mov_b32_e32 v67, v0
	v_mov_b32_e32 v68, v0
	v_mov_b32_e32 v69, v0
	v_mov_b32_e32 v70, v0
	v_mov_b32_e32 v71, v0
	v_mov_b32_e32 v80, v0
	v_mov_b32_e32 v81, v0
	v_mov_b32_e32 v82, v0
	v_mov_b32_e32 v83, v0
	v_mov_b32_e32 v84, v0
	v_mov_b32_e32 v85, v0
	v_mov_b32_e32 v86, v0
	v_mov_b32_e32 v87, v0
	v_mov_b32_e32 v96, v0
	v_mov_b32_e32 v97, v0
	v_mov_b32_e32 v98, v0
	v_mov_b32_e32 v99, v0
	v_mov_b32_e32 v100, v0
	v_mov_b32_e32 v101, v0
	v_mov_b32_e32 v102, v0
	v_mov_b32_e32 v103, v0
	v_mov_b32_e32 v112, v0
	v_mov_b32_e32 v113, v0
	v_mov_b32_e32 v114, v0
	v_mov_b32_e32 v115, v0
	v_mov_b32_e32 v116, v0
	v_mov_b32_e32 v117, v0
	v_mov_b32_e32 v118, v0
	v_mov_b32_e32 v119, v0
	v_mov_b32_e32 v72, v0
	v_mov_b32_e32 v73, v0
	v_mov_b32_e32 v74, v0
	v_mov_b32_e32 v75, v0
	v_mov_b32_e32 v76, v0
	v_mov_b32_e32 v77, v0
	v_mov_b32_e32 v78, v0
	v_mov_b32_e32 v79, v0
	v_mov_b32_e32 v88, v0
	v_mov_b32_e32 v89, v0
	v_mov_b32_e32 v90, v0
	v_mov_b32_e32 v91, v0
	v_mov_b32_e32 v92, v0
	v_mov_b32_e32 v93, v0
	v_mov_b32_e32 v94, v0
	v_mov_b32_e32 v95, v0
	v_mov_b32_e32 v104, v0
	v_mov_b32_e32 v105, v0
	v_mov_b32_e32 v106, v0
	v_mov_b32_e32 v107, v0
	v_mov_b32_e32 v108, v0
	v_mov_b32_e32 v109, v0
	v_mov_b32_e32 v110, v0
	v_mov_b32_e32 v111, v0
	v_mov_b32_e32 v120, v0
	v_mov_b32_e32 v121, v0
	v_mov_b32_e32 v122, v0
	v_mov_b32_e32 v123, v0
	v_mov_b32_e32 v124, v0
	v_mov_b32_e32 v125, v0
	v_mov_b32_e32 v126, v0
	v_mov_b32_e32 v127, v0
	.p2alignl 6, 3212836864

.LBB0_782:
	s_ashr_i32 s41, s40, 31
	s_lshl_b64 s[42:43], s[40:41], 21
	s_add_u32 s42, s54, s42
	s_addc_u32 s43, s55, s43
	s_and_b64 s[44:45], s[6:7], exec
	s_cselect_b32 s9, s43, s49
	s_cselect_b32 s41, s42, s48
	s_ashr_i32 s39, s38, 31
	s_lshl_b64 s[44:45], s[38:39], 21
	s_add_u32 s44, s56, s44
	s_addc_u32 s45, s57, s45
	s_and_b64 s[52:53], s[6:7], exec
	s_cselect_b32 s39, s45, s51
	s_cselect_b32 s47, s44, s50
	s_add_u32 s48, s48, 0x100080
	s_addc_u32 s49, s49, 0
	s_add_u32 s71, s50, 0x100
	v_mov_b32_e32 v0, 0
	s_addc_u32 s72, s51, 0
	s_mov_b32 s73, -2
	v_mov_b32_e32 v1, v0
	v_mov_b32_e32 v2, v0
	v_mov_b32_e32 v3, v0
	v_mov_b32_e32 v4, v0
	v_mov_b32_e32 v5, v0
	v_mov_b32_e32 v6, v0
	v_mov_b32_e32 v7, v0
	v_mov_b32_e32 v16, v0
	v_mov_b32_e32 v17, v0
	v_mov_b32_e32 v18, v0
	v_mov_b32_e32 v19, v0
	v_mov_b32_e32 v20, v0
	v_mov_b32_e32 v21, v0
	v_mov_b32_e32 v22, v0
	v_mov_b32_e32 v23, v0
	v_mov_b32_e32 v32, v0
	v_mov_b32_e32 v33, v0
	v_mov_b32_e32 v34, v0
	v_mov_b32_e32 v35, v0
	v_mov_b32_e32 v36, v0
	v_mov_b32_e32 v37, v0
	v_mov_b32_e32 v38, v0
	v_mov_b32_e32 v39, v0
	v_mov_b32_e32 v48, v0
	v_mov_b32_e32 v49, v0
	v_mov_b32_e32 v50, v0
	v_mov_b32_e32 v51, v0
	v_mov_b32_e32 v52, v0
	v_mov_b32_e32 v53, v0
	v_mov_b32_e32 v54, v0
	v_mov_b32_e32 v55, v0
	v_mov_b32_e32 v8, v0
	v_mov_b32_e32 v9, v0
	v_mov_b32_e32 v10, v0
	v_mov_b32_e32 v11, v0
	v_mov_b32_e32 v12, v0
	v_mov_b32_e32 v13, v0
	v_mov_b32_e32 v14, v0
	v_mov_b32_e32 v15, v0
	v_mov_b32_e32 v24, v0
	v_mov_b32_e32 v25, v0
	v_mov_b32_e32 v26, v0
	v_mov_b32_e32 v27, v0
	v_mov_b32_e32 v28, v0
	v_mov_b32_e32 v29, v0
	v_mov_b32_e32 v30, v0
	v_mov_b32_e32 v31, v0
	v_mov_b32_e32 v40, v0
	v_mov_b32_e32 v41, v0
	v_mov_b32_e32 v42, v0
	v_mov_b32_e32 v43, v0
	v_mov_b32_e32 v44, v0
	v_mov_b32_e32 v45, v0
	v_mov_b32_e32 v46, v0
	v_mov_b32_e32 v47, v0
	v_mov_b32_e32 v56, v0
	v_mov_b32_e32 v57, v0
	v_mov_b32_e32 v58, v0
	v_mov_b32_e32 v59, v0
	v_mov_b32_e32 v60, v0
	v_mov_b32_e32 v61, v0
	v_mov_b32_e32 v62, v0
	v_mov_b32_e32 v63, v0
	v_mov_b32_e32 v64, v0
	v_mov_b32_e32 v65, v0
	v_mov_b32_e32 v66, v0
	v_mov_b32_e32 v67, v0
	v_mov_b32_e32 v68, v0
	v_mov_b32_e32 v69, v0
	v_mov_b32_e32 v70, v0
	v_mov_b32_e32 v71, v0
	v_mov_b32_e32 v80, v0
	v_mov_b32_e32 v81, v0
	v_mov_b32_e32 v82, v0
	v_mov_b32_e32 v83, v0
	v_mov_b32_e32 v84, v0
	v_mov_b32_e32 v85, v0
	v_mov_b32_e32 v86, v0
	v_mov_b32_e32 v87, v0
	v_mov_b32_e32 v96, v0
	v_mov_b32_e32 v97, v0
	v_mov_b32_e32 v98, v0
	v_mov_b32_e32 v99, v0
	v_mov_b32_e32 v100, v0
	v_mov_b32_e32 v101, v0
	v_mov_b32_e32 v102, v0
	v_mov_b32_e32 v103, v0
	v_mov_b32_e32 v112, v0
	v_mov_b32_e32 v113, v0
	v_mov_b32_e32 v114, v0
	v_mov_b32_e32 v115, v0
	v_mov_b32_e32 v116, v0
	v_mov_b32_e32 v117, v0
	v_mov_b32_e32 v118, v0
	v_mov_b32_e32 v119, v0
	v_mov_b32_e32 v72, v0
	v_mov_b32_e32 v73, v0
	v_mov_b32_e32 v74, v0
	v_mov_b32_e32 v75, v0
	v_mov_b32_e32 v76, v0
	v_mov_b32_e32 v77, v0
	v_mov_b32_e32 v78, v0
	v_mov_b32_e32 v79, v0
	v_mov_b32_e32 v88, v0
	v_mov_b32_e32 v89, v0
	v_mov_b32_e32 v90, v0
	v_mov_b32_e32 v91, v0
	v_mov_b32_e32 v92, v0
	v_mov_b32_e32 v93, v0
	v_mov_b32_e32 v94, v0
	v_mov_b32_e32 v95, v0
	v_mov_b32_e32 v104, v0
	v_mov_b32_e32 v105, v0
	v_mov_b32_e32 v106, v0
	v_mov_b32_e32 v107, v0
	v_mov_b32_e32 v108, v0
	v_mov_b32_e32 v109, v0
	v_mov_b32_e32 v110, v0
	v_mov_b32_e32 v111, v0
	v_mov_b32_e32 v120, v0
	v_mov_b32_e32 v121, v0
	v_mov_b32_e32 v122, v0
	v_mov_b32_e32 v123, v0
	v_mov_b32_e32 v124, v0
	v_mov_b32_e32 v125, v0
	v_mov_b32_e32 v126, v0
	v_mov_b32_e32 v127, v0
	.p2alignl 6, 3212836864

.LBB0_901:
	s_ashr_i32 s19, s18, 31
	s_lshl_b64 s[20:21], s[18:19], 19
	s_add_u32 s20, s43, s20
	s_addc_u32 s21, s44, s21
	s_and_b64 s[22:23], s[4:5], exec
	s_cselect_b32 s19, s21, s37
	s_cselect_b32 s61, s20, s36
	s_ashr_i32 s17, s16, 31
	s_lshl_b64 s[22:23], s[16:17], 19
	s_add_u32 s22, s45, s22
	s_addc_u32 s23, s46, s23
	s_and_b64 s[40:41], s[4:5], exec
	s_cselect_b32 s17, s23, s39
	s_cselect_b32 s62, s22, s38
	s_add_u32 s36, s36, 0x40080
	s_addc_u32 s37, s37, 0
	s_add_u32 s63, s38, 0x100
	v_mov_b32_e32 v0, 0
	s_addc_u32 s64, s39, 0
	s_mov_b32 s65, -2
	v_mov_b32_e32 v1, v0
	v_mov_b32_e32 v2, v0
	v_mov_b32_e32 v3, v0
	v_mov_b32_e32 v4, v0
	v_mov_b32_e32 v5, v0
	v_mov_b32_e32 v6, v0
	v_mov_b32_e32 v7, v0
	v_mov_b32_e32 v16, v0
	v_mov_b32_e32 v17, v0
	v_mov_b32_e32 v18, v0
	v_mov_b32_e32 v19, v0
	v_mov_b32_e32 v20, v0
	v_mov_b32_e32 v21, v0
	v_mov_b32_e32 v22, v0
	v_mov_b32_e32 v23, v0
	v_mov_b32_e32 v32, v0
	v_mov_b32_e32 v33, v0
	v_mov_b32_e32 v34, v0
	v_mov_b32_e32 v35, v0
	v_mov_b32_e32 v36, v0
	v_mov_b32_e32 v37, v0
	v_mov_b32_e32 v38, v0
	v_mov_b32_e32 v39, v0
	v_mov_b32_e32 v48, v0
	v_mov_b32_e32 v49, v0
	v_mov_b32_e32 v50, v0
	v_mov_b32_e32 v51, v0
	v_mov_b32_e32 v52, v0
	v_mov_b32_e32 v53, v0
	v_mov_b32_e32 v54, v0
	v_mov_b32_e32 v55, v0
	v_mov_b32_e32 v8, v0
	v_mov_b32_e32 v9, v0
	v_mov_b32_e32 v10, v0
	v_mov_b32_e32 v11, v0
	v_mov_b32_e32 v12, v0
	v_mov_b32_e32 v13, v0
	v_mov_b32_e32 v14, v0
	v_mov_b32_e32 v15, v0
	v_mov_b32_e32 v24, v0
	v_mov_b32_e32 v25, v0
	v_mov_b32_e32 v26, v0
	v_mov_b32_e32 v27, v0
	v_mov_b32_e32 v28, v0
	v_mov_b32_e32 v29, v0
	v_mov_b32_e32 v30, v0
	v_mov_b32_e32 v31, v0
	v_mov_b32_e32 v40, v0
	v_mov_b32_e32 v41, v0
	v_mov_b32_e32 v42, v0
	v_mov_b32_e32 v43, v0
	v_mov_b32_e32 v44, v0
	v_mov_b32_e32 v45, v0
	v_mov_b32_e32 v46, v0
	v_mov_b32_e32 v47, v0
	v_mov_b32_e32 v56, v0
	v_mov_b32_e32 v57, v0
	v_mov_b32_e32 v58, v0
	v_mov_b32_e32 v59, v0
	v_mov_b32_e32 v60, v0
	v_mov_b32_e32 v61, v0
	v_mov_b32_e32 v62, v0
	v_mov_b32_e32 v63, v0
	v_mov_b32_e32 v64, v0
	v_mov_b32_e32 v65, v0
	v_mov_b32_e32 v66, v0
	v_mov_b32_e32 v67, v0
	v_mov_b32_e32 v68, v0
	v_mov_b32_e32 v69, v0
	v_mov_b32_e32 v70, v0
	v_mov_b32_e32 v71, v0
	v_mov_b32_e32 v80, v0
	v_mov_b32_e32 v81, v0
	v_mov_b32_e32 v82, v0
	v_mov_b32_e32 v83, v0
	v_mov_b32_e32 v84, v0
	v_mov_b32_e32 v85, v0
	v_mov_b32_e32 v86, v0
	v_mov_b32_e32 v87, v0
	v_mov_b32_e32 v96, v0
	v_mov_b32_e32 v97, v0
	v_mov_b32_e32 v98, v0
	v_mov_b32_e32 v99, v0
	v_mov_b32_e32 v100, v0
	v_mov_b32_e32 v101, v0
	v_mov_b32_e32 v102, v0
	v_mov_b32_e32 v103, v0
	v_mov_b32_e32 v112, v0
	v_mov_b32_e32 v113, v0
	v_mov_b32_e32 v114, v0
	v_mov_b32_e32 v115, v0
	v_mov_b32_e32 v116, v0
	v_mov_b32_e32 v117, v0
	v_mov_b32_e32 v118, v0
	v_mov_b32_e32 v119, v0
	v_mov_b32_e32 v72, v0
	v_mov_b32_e32 v73, v0
	v_mov_b32_e32 v74, v0
	v_mov_b32_e32 v75, v0
	v_mov_b32_e32 v76, v0
	v_mov_b32_e32 v77, v0
	v_mov_b32_e32 v78, v0
	v_mov_b32_e32 v79, v0
	v_mov_b32_e32 v88, v0
	v_mov_b32_e32 v89, v0
	v_mov_b32_e32 v90, v0
	v_mov_b32_e32 v91, v0
	v_mov_b32_e32 v92, v0
	v_mov_b32_e32 v93, v0
	v_mov_b32_e32 v94, v0
	v_mov_b32_e32 v95, v0
	v_mov_b32_e32 v104, v0
	v_mov_b32_e32 v105, v0
	v_mov_b32_e32 v106, v0
	v_mov_b32_e32 v107, v0
	v_mov_b32_e32 v108, v0
	v_mov_b32_e32 v109, v0
	v_mov_b32_e32 v110, v0
	v_mov_b32_e32 v111, v0
	v_mov_b32_e32 v120, v0
	v_mov_b32_e32 v121, v0
	v_mov_b32_e32 v122, v0
	v_mov_b32_e32 v123, v0
	v_mov_b32_e32 v124, v0
	v_mov_b32_e32 v125, v0
	v_mov_b32_e32 v126, v0
	v_mov_b32_e32 v127, v0
	.p2alignl 6, 3212836864

.LBB0_1226:
	s_ashr_i32 s23, s22, 31
	s_lshl_b64 s[24:25], s[22:23], 19
	s_add_u32 s24, s48, s24
	s_addc_u32 s25, s49, s25
	s_and_b64 s[36:37], s[6:7], exec
	s_cselect_b32 s23, s25, s43
	s_cselect_b32 s39, s24, s42
	s_ashr_i32 s21, s20, 31
	s_lshl_b64 s[36:37], s[20:21], 19
	s_add_u32 s36, s50, s36
	s_addc_u32 s37, s51, s37
	s_and_b64 s[46:47], s[6:7], exec
	s_cselect_b32 s21, s37, s45
	s_cselect_b32 s64, s36, s44
	s_add_u32 s42, s42, 0x40080
	s_addc_u32 s43, s43, 0
	s_add_u32 s65, s44, 0x100
	v_mov_b32_e32 v4, 0
	s_addc_u32 s66, s45, 0
	s_mov_b32 s67, -2
	v_mov_b32_e32 v5, v4
	v_mov_b32_e32 v6, v4
	v_mov_b32_e32 v7, v4
	v_mov_b32_e32 v12, v4
	v_mov_b32_e32 v13, v4
	v_mov_b32_e32 v14, v4
	v_mov_b32_e32 v15, v4
	v_mov_b32_e32 v20, v4
	v_mov_b32_e32 v21, v4
	v_mov_b32_e32 v22, v4
	v_mov_b32_e32 v23, v4
	v_mov_b32_e32 v28, v4
	v_mov_b32_e32 v29, v4
	v_mov_b32_e32 v30, v4
	v_mov_b32_e32 v31, v4
	v_mov_b32_e32 v36, v4
	v_mov_b32_e32 v37, v4
	v_mov_b32_e32 v38, v4
	v_mov_b32_e32 v39, v4
	v_mov_b32_e32 v44, v4
	v_mov_b32_e32 v45, v4
	v_mov_b32_e32 v46, v4
	v_mov_b32_e32 v47, v4
	v_mov_b32_e32 v52, v4
	v_mov_b32_e32 v53, v4
	v_mov_b32_e32 v54, v4
	v_mov_b32_e32 v55, v4
	v_mov_b32_e32 v60, v4
	v_mov_b32_e32 v61, v4
	v_mov_b32_e32 v62, v4
	v_mov_b32_e32 v63, v4
	v_mov_b32_e32 v0, v4
	v_mov_b32_e32 v1, v4
	v_mov_b32_e32 v2, v4
	v_mov_b32_e32 v3, v4
	v_mov_b32_e32 v8, v4
	v_mov_b32_e32 v9, v4
	v_mov_b32_e32 v10, v4
	v_mov_b32_e32 v11, v4
	v_mov_b32_e32 v16, v4
	v_mov_b32_e32 v17, v4
	v_mov_b32_e32 v18, v4
	v_mov_b32_e32 v19, v4
	v_mov_b32_e32 v24, v4
	v_mov_b32_e32 v25, v4
	v_mov_b32_e32 v26, v4
	v_mov_b32_e32 v27, v4
	v_mov_b32_e32 v32, v4
	v_mov_b32_e32 v33, v4
	v_mov_b32_e32 v34, v4
	v_mov_b32_e32 v35, v4
	v_mov_b32_e32 v40, v4
	v_mov_b32_e32 v41, v4
	v_mov_b32_e32 v42, v4
	v_mov_b32_e32 v43, v4
	v_mov_b32_e32 v48, v4
	v_mov_b32_e32 v49, v4
	v_mov_b32_e32 v50, v4
	v_mov_b32_e32 v51, v4
	v_mov_b32_e32 v56, v4
	v_mov_b32_e32 v57, v4
	v_mov_b32_e32 v58, v4
	v_mov_b32_e32 v59, v4
	v_mov_b32_e32 v68, v4
	v_mov_b32_e32 v69, v4
	v_mov_b32_e32 v70, v4
	v_mov_b32_e32 v71, v4
	v_mov_b32_e32 v76, v4
	v_mov_b32_e32 v77, v4
	v_mov_b32_e32 v78, v4
	v_mov_b32_e32 v79, v4
	v_mov_b32_e32 v84, v4
	v_mov_b32_e32 v85, v4
	v_mov_b32_e32 v86, v4
	v_mov_b32_e32 v87, v4
	v_mov_b32_e32 v92, v4
	v_mov_b32_e32 v93, v4
	v_mov_b32_e32 v94, v4
	v_mov_b32_e32 v95, v4
	v_mov_b32_e32 v100, v4
	v_mov_b32_e32 v101, v4
	v_mov_b32_e32 v102, v4
	v_mov_b32_e32 v103, v4
	v_mov_b32_e32 v108, v4
	v_mov_b32_e32 v109, v4
	v_mov_b32_e32 v110, v4
	v_mov_b32_e32 v111, v4
	v_mov_b32_e32 v116, v4
	v_mov_b32_e32 v117, v4
	v_mov_b32_e32 v118, v4
	v_mov_b32_e32 v119, v4
	v_mov_b32_e32 v124, v4
	v_mov_b32_e32 v125, v4
	v_mov_b32_e32 v126, v4
	v_mov_b32_e32 v127, v4
	v_mov_b32_e32 v64, v4
	v_mov_b32_e32 v65, v4
	v_mov_b32_e32 v66, v4
	v_mov_b32_e32 v67, v4
	v_mov_b32_e32 v72, v4
	v_mov_b32_e32 v73, v4
	v_mov_b32_e32 v74, v4
	v_mov_b32_e32 v75, v4
	v_mov_b32_e32 v80, v4
	v_mov_b32_e32 v81, v4
	v_mov_b32_e32 v82, v4
	v_mov_b32_e32 v83, v4
	v_mov_b32_e32 v88, v4
	v_mov_b32_e32 v89, v4
	v_mov_b32_e32 v90, v4
	v_mov_b32_e32 v91, v4
	v_mov_b32_e32 v96, v4
	v_mov_b32_e32 v97, v4
	v_mov_b32_e32 v98, v4
	v_mov_b32_e32 v99, v4
	v_mov_b32_e32 v104, v4
	v_mov_b32_e32 v105, v4
	v_mov_b32_e32 v106, v4
	v_mov_b32_e32 v107, v4
	v_mov_b32_e32 v112, v4
	v_mov_b32_e32 v113, v4
	v_mov_b32_e32 v114, v4
	v_mov_b32_e32 v115, v4
	v_mov_b32_e32 v120, v4
	v_mov_b32_e32 v121, v4
	v_mov_b32_e32 v122, v4
	v_mov_b32_e32 v123, v4
	.p2alignl 6, 3212836864

.LBB0_1401:
	s_ashr_i32 s31, s30, 31
	s_lshl_b64 s[34:35], s[30:31], 21
	s_add_u32 s34, s29, s34
	s_addc_u32 s35, s33, s35
	s_and_b64 s[36:37], s[0:1], exec
	s_cselect_b32 s31, s35, s41
	s_cselect_b32 s59, s34, s40
	s_ashr_i32 s27, s26, 31
	s_lshl_b64 s[36:37], s[26:27], 21
	s_add_u32 s36, s46, s36
	s_addc_u32 s37, s47, s37
	s_and_b64 s[44:45], s[0:1], exec
	s_cselect_b32 s27, s37, s43
	s_cselect_b32 s60, s36, s42
	s_add_u32 s40, s40, 0x100080
	s_addc_u32 s41, s41, 0
	s_add_u32 s61, s42, 0x100
	v_mov_b32_e32 v0, 0
	s_addc_u32 s62, s43, 0
	s_mov_b32 s63, -2
	v_mov_b32_e32 v1, v0
	v_mov_b32_e32 v2, v0
	v_mov_b32_e32 v3, v0
	v_mov_b32_e32 v4, v0
	v_mov_b32_e32 v5, v0
	v_mov_b32_e32 v6, v0
	v_mov_b32_e32 v7, v0
	v_mov_b32_e32 v16, v0
	v_mov_b32_e32 v17, v0
	v_mov_b32_e32 v18, v0
	v_mov_b32_e32 v19, v0
	v_mov_b32_e32 v20, v0
	v_mov_b32_e32 v21, v0
	v_mov_b32_e32 v22, v0
	v_mov_b32_e32 v23, v0
	v_mov_b32_e32 v32, v0
	v_mov_b32_e32 v33, v0
	v_mov_b32_e32 v34, v0
	v_mov_b32_e32 v35, v0
	v_mov_b32_e32 v36, v0
	v_mov_b32_e32 v37, v0
	v_mov_b32_e32 v38, v0
	v_mov_b32_e32 v39, v0
	v_mov_b32_e32 v48, v0
	v_mov_b32_e32 v49, v0
	v_mov_b32_e32 v50, v0
	v_mov_b32_e32 v51, v0
	v_mov_b32_e32 v52, v0
	v_mov_b32_e32 v53, v0
	v_mov_b32_e32 v54, v0
	v_mov_b32_e32 v55, v0
	v_mov_b32_e32 v12, v0
	v_mov_b32_e32 v13, v0
	v_mov_b32_e32 v14, v0
	v_mov_b32_e32 v15, v0
	v_mov_b32_e32 v8, v0
	v_mov_b32_e32 v9, v0
	v_mov_b32_e32 v10, v0
	v_mov_b32_e32 v11, v0
	v_mov_b32_e32 v28, v0
	v_mov_b32_e32 v29, v0
	v_mov_b32_e32 v30, v0
	v_mov_b32_e32 v31, v0
	v_mov_b32_e32 v24, v0
	v_mov_b32_e32 v25, v0
	v_mov_b32_e32 v26, v0
	v_mov_b32_e32 v27, v0
	v_mov_b32_e32 v44, v0
	v_mov_b32_e32 v45, v0
	v_mov_b32_e32 v46, v0
	v_mov_b32_e32 v47, v0
	v_mov_b32_e32 v40, v0
	v_mov_b32_e32 v41, v0
	v_mov_b32_e32 v42, v0
	v_mov_b32_e32 v43, v0
	v_mov_b32_e32 v60, v0
	v_mov_b32_e32 v61, v0
	v_mov_b32_e32 v62, v0
	v_mov_b32_e32 v63, v0
	v_mov_b32_e32 v56, v0
	v_mov_b32_e32 v57, v0
	v_mov_b32_e32 v58, v0
	v_mov_b32_e32 v59, v0
	v_mov_b32_e32 v64, v0
	v_mov_b32_e32 v65, v0
	v_mov_b32_e32 v66, v0
	v_mov_b32_e32 v67, v0
	v_mov_b32_e32 v68, v0
	v_mov_b32_e32 v69, v0
	v_mov_b32_e32 v70, v0
	v_mov_b32_e32 v71, v0
	v_mov_b32_e32 v80, v0
	v_mov_b32_e32 v81, v0
	v_mov_b32_e32 v82, v0
	v_mov_b32_e32 v83, v0
	v_mov_b32_e32 v84, v0
	v_mov_b32_e32 v85, v0
	v_mov_b32_e32 v86, v0
	v_mov_b32_e32 v87, v0
	v_mov_b32_e32 v96, v0
	v_mov_b32_e32 v97, v0
	v_mov_b32_e32 v98, v0
	v_mov_b32_e32 v99, v0
	v_mov_b32_e32 v100, v0
	v_mov_b32_e32 v101, v0
	v_mov_b32_e32 v102, v0
	v_mov_b32_e32 v103, v0
	v_mov_b32_e32 v112, v0
	v_mov_b32_e32 v113, v0
	v_mov_b32_e32 v114, v0
	v_mov_b32_e32 v115, v0
	v_mov_b32_e32 v116, v0
	v_mov_b32_e32 v117, v0
	v_mov_b32_e32 v118, v0
	v_mov_b32_e32 v119, v0
	v_mov_b32_e32 v76, v0
	v_mov_b32_e32 v77, v0
	v_mov_b32_e32 v78, v0
	v_mov_b32_e32 v79, v0
	v_mov_b32_e32 v72, v0
	v_mov_b32_e32 v73, v0
	v_mov_b32_e32 v74, v0
	v_mov_b32_e32 v75, v0
	v_mov_b32_e32 v92, v0
	v_mov_b32_e32 v93, v0
	v_mov_b32_e32 v94, v0
	v_mov_b32_e32 v95, v0
	v_mov_b32_e32 v88, v0
	v_mov_b32_e32 v89, v0
	v_mov_b32_e32 v90, v0
	v_mov_b32_e32 v91, v0
	v_mov_b32_e32 v108, v0
	v_mov_b32_e32 v109, v0
	v_mov_b32_e32 v110, v0
	v_mov_b32_e32 v111, v0
	v_mov_b32_e32 v104, v0
	v_mov_b32_e32 v105, v0
	v_mov_b32_e32 v106, v0
	v_mov_b32_e32 v107, v0
	v_mov_b32_e32 v124, v0
	v_mov_b32_e32 v125, v0
	v_mov_b32_e32 v126, v0
	v_mov_b32_e32 v127, v0
	v_mov_b32_e32 v120, v0
	v_mov_b32_e32 v121, v0
	v_mov_b32_e32 v122, v0
	v_mov_b32_e32 v123, v0
	.p2alignl 6, 3212836864
